# hyena block-Toeplitz MFMA loops software-pipelined (next step's LDS fragments read under the current MFMAs, two register sets, no per-step exec branch)
# speedup vs baseline: 1.0089x; 1.0089x over previous
.LBB0_1068:
	s_and_b64 s[20:21], exec, s[44:45]
	v_add_u32_e32 v122, 0xfffffe00, v44
	s_cbranch_scc0 .Lhy1_1068
	ds_read_b128 v[46:49], v122 offset:512
	ds_read_b128 v[34:37], v43
	ds_read_b128 v[106:109], v122 offset:16896
	s_lshr_b32 s4, s4, 1
	s_add_i32 s4, s4, -1
	s_cmp_eq_u32 s4, 0
	s_cbranch_scc1 .Lhy2_tail_1068
.Lhy2_loop_1068:
	ds_read_b128 v[110:113], v122 offset:256
	ds_read_b128 v[114:117], v43 offset:32
	ds_read_b128 v[118:121], v122 offset:16640
	s_waitcnt lgkmcnt(3)
	v_mfma_f32_32x32x16_bf16 v[18:33], v[46:49], v[34:37], v[18:33]
	v_mfma_f32_32x32x16_bf16 v[2:17], v[106:109], v[34:37], v[2:17]
	ds_read_b128 v[46:49], v122
	ds_read_b128 v[34:37], v43 offset:64
	ds_read_b128 v[106:109], v122 offset:16384
	v_add_u32_e32 v122, 0xfffffe00, v122
	v_add_u32_e32 v43, 64, v43
	s_add_i32 s4, s4, -1
	s_waitcnt lgkmcnt(3)
	v_mfma_f32_32x32x16_bf16 v[18:33], v[110:113], v[114:117], v[18:33]
	v_mfma_f32_32x32x16_bf16 v[2:17], v[118:121], v[114:117], v[2:17]
	s_cmp_eq_u32 s4, 0
	s_cbranch_scc0 .Lhy2_loop_1068
.Lhy2_tail_1068:
	ds_read_b128 v[110:113], v122 offset:256
	ds_read_b128 v[114:117], v43 offset:32
	ds_read_b128 v[118:121], v122 offset:16640
	s_waitcnt lgkmcnt(3)
	v_mfma_f32_32x32x16_bf16 v[18:33], v[46:49], v[34:37], v[18:33]
	v_mfma_f32_32x32x16_bf16 v[2:17], v[106:109], v[34:37], v[2:17]
	s_waitcnt lgkmcnt(0)
	v_mfma_f32_32x32x16_bf16 v[18:33], v[110:113], v[114:117], v[18:33]
	v_mfma_f32_32x32x16_bf16 v[2:17], v[118:121], v[114:117], v[2:17]
	s_branch .LBB0_1070
.Lhy1_1068:
	ds_read_b128 v[46:49], v122 offset:512
	ds_read_b128 v[34:37], v43
	s_lshr_b32 s4, s4, 1
	s_add_i32 s4, s4, -1
	s_cmp_eq_u32 s4, 0
	s_cbranch_scc1 .Lhy1_tail_1068
.Lhy1_loop_1068:
	ds_read_b128 v[110:113], v122 offset:256
	ds_read_b128 v[114:117], v43 offset:32
	s_waitcnt lgkmcnt(2)
	v_mfma_f32_32x32x16_bf16 v[18:33], v[46:49], v[34:37], v[18:33]
	ds_read_b128 v[46:49], v122
	ds_read_b128 v[34:37], v43 offset:64
	v_add_u32_e32 v122, 0xfffffe00, v122
	v_add_u32_e32 v43, 64, v43
	s_add_i32 s4, s4, -1
	s_waitcnt lgkmcnt(2)
	v_mfma_f32_32x32x16_bf16 v[18:33], v[110:113], v[114:117], v[18:33]
	s_cmp_eq_u32 s4, 0
	s_cbranch_scc0 .Lhy1_loop_1068
.Lhy1_tail_1068:
	ds_read_b128 v[110:113], v122 offset:256
	ds_read_b128 v[114:117], v43 offset:32
	s_waitcnt lgkmcnt(2)
	v_mfma_f32_32x32x16_bf16 v[18:33], v[46:49], v[34:37], v[18:33]
	s_waitcnt lgkmcnt(0)
	v_mfma_f32_32x32x16_bf16 v[18:33], v[110:113], v[114:117], v[18:33]

.LBB0_1189:
	s_and_b64 s[20:21], exec, s[44:45]
	v_add_u32_e32 v122, 0xfffffe00, v44
	s_cbranch_scc0 .Lhy1_1189
	ds_read_b128 v[46:49], v122 offset:512
	ds_read_b128 v[34:37], v39
	ds_read_b128 v[106:109], v122 offset:16896
	s_lshr_b32 s4, s4, 1
	s_add_i32 s4, s4, -1
	s_cmp_eq_u32 s4, 0
	s_cbranch_scc1 .Lhy2_tail_1189
.Lhy2_loop_1189:
	ds_read_b128 v[110:113], v122 offset:256
	ds_read_b128 v[114:117], v39 offset:32
	ds_read_b128 v[118:121], v122 offset:16640
	s_waitcnt lgkmcnt(3)
	v_mfma_f32_32x32x16_bf16 v[18:33], v[46:49], v[34:37], v[18:33]
	v_mfma_f32_32x32x16_bf16 v[2:17], v[106:109], v[34:37], v[2:17]
	ds_read_b128 v[46:49], v122
	ds_read_b128 v[34:37], v39 offset:64
	ds_read_b128 v[106:109], v122 offset:16384
	v_add_u32_e32 v122, 0xfffffe00, v122
	v_add_u32_e32 v39, 64, v39
	s_add_i32 s4, s4, -1
	s_waitcnt lgkmcnt(3)
	v_mfma_f32_32x32x16_bf16 v[18:33], v[110:113], v[114:117], v[18:33]
	v_mfma_f32_32x32x16_bf16 v[2:17], v[118:121], v[114:117], v[2:17]
	s_cmp_eq_u32 s4, 0
	s_cbranch_scc0 .Lhy2_loop_1189
.Lhy2_tail_1189:
	ds_read_b128 v[110:113], v122 offset:256
	ds_read_b128 v[114:117], v39 offset:32
	ds_read_b128 v[118:121], v122 offset:16640
	s_waitcnt lgkmcnt(3)
	v_mfma_f32_32x32x16_bf16 v[18:33], v[46:49], v[34:37], v[18:33]
	v_mfma_f32_32x32x16_bf16 v[2:17], v[106:109], v[34:37], v[2:17]
	s_waitcnt lgkmcnt(0)
	v_mfma_f32_32x32x16_bf16 v[18:33], v[110:113], v[114:117], v[18:33]
	v_mfma_f32_32x32x16_bf16 v[2:17], v[118:121], v[114:117], v[2:17]
	s_branch .LBB0_1191
.Lhy1_1189:
	ds_read_b128 v[46:49], v122 offset:512
	ds_read_b128 v[34:37], v39
	s_lshr_b32 s4, s4, 1
	s_add_i32 s4, s4, -1
	s_cmp_eq_u32 s4, 0
	s_cbranch_scc1 .Lhy1_tail_1189
.Lhy1_loop_1189:
	ds_read_b128 v[110:113], v122 offset:256
	ds_read_b128 v[114:117], v39 offset:32
	s_waitcnt lgkmcnt(2)
	v_mfma_f32_32x32x16_bf16 v[18:33], v[46:49], v[34:37], v[18:33]
	ds_read_b128 v[46:49], v122
	ds_read_b128 v[34:37], v39 offset:64
	v_add_u32_e32 v122, 0xfffffe00, v122
	v_add_u32_e32 v39, 64, v39
	s_add_i32 s4, s4, -1
	s_waitcnt lgkmcnt(2)
	v_mfma_f32_32x32x16_bf16 v[18:33], v[110:113], v[114:117], v[18:33]
	s_cmp_eq_u32 s4, 0
	s_cbranch_scc0 .Lhy1_loop_1189
.Lhy1_tail_1189:
	ds_read_b128 v[110:113], v122 offset:256
	ds_read_b128 v[114:117], v39 offset:32
	s_waitcnt lgkmcnt(2)
	v_mfma_f32_32x32x16_bf16 v[18:33], v[46:49], v[34:37], v[18:33]
	s_waitcnt lgkmcnt(0)
	v_mfma_f32_32x32x16_bf16 v[18:33], v[110:113], v[114:117], v[18:33]
